# v16 + S5 prologue matrices: kt on f32 matrix cores (v_mfma_f32_16x16x4_f32, 2 j per wave) and W2 block written with 16-byte stores, both hand-written
# speedup vs baseline: 1.1626x; 1.0055x over previous
; __global__ void __launch_bounds__(NWAVES * 64, 2) fwd_kernel(Args args) {
;     ...
;             for (int idx = tid; idx < 1024; idx += 512) { cc[idx * 2] = c_re[(size_t)lg * 1024 + idx]; cc[idx * 2 + 1] = c_im[(size_t)lg * 1024 + idx]; }
;             __syncthreads();
;             for (int idx = tid; idx < 4096; idx += 512) { const int j = idx >> 8, p = (idx >> 4) & 15, q = idx & 15; float sum = 0.f;
;                 for (int n = 0; n < 64; ++n) { const float cr = cc[(p * 64 + n) * 2], ci = cc[(p * 64 + n) * 2 + 1], ar = ap[(j * 64 + n) * 2], ai = ap[(j * 64 + n) * 2 + 1];
;                     const float tr = cr * ar - ci * ai, ti = cr * ai + ci * ar; sum += tr * bb[(n * 16 + q) * 2] - ti * bb[(n * 16 + q) * 2 + 1]; }
;                 if (j == 0 && p == q) sum += ssm_d[lg * 16 + p];
;                 kt[idx] = sum; }
.LBB0_35:
	global_load_dword v20, v[14:15], off
	global_load_dword v21, v[16:17], off
	v_add_co_u32_e32 v18, vcc, 0x200, v18
	s_xor_b64 s[26:27], vcc, -1
	s_and_b64 s[26:27], exec, s[26:27]
	v_lshl_add_u64 v[16:17], v[16:17], 0, s[14:15]
	v_lshl_add_u64 v[14:15], v[14:15], 0, s[14:15]
	s_or_b64 s[0:1], s[26:27], s[0:1]
	s_waitcnt vmcnt(0)
	ds_write_b64 v10, v[20:21]
	v_add_u32_e32 v10, 0x1000, v10
	s_andn2_b64 exec, exec, s[0:1]
	s_cbranch_execnz .LBB0_35
	s_or_b64 exec, exec, s[0:1]
	s_lshl_b32 s25, s24, 4
	s_mov_b64 s[0:1], 0
	v_mov_b32_e32 v10, v27
	v_mov_b32_e32 v14, v38
	s_waitcnt lgkmcnt(0)
	s_barrier
	v_mbcnt_lo_u32_b32 v144, -1, 0
	v_mbcnt_hi_u32_b32 v144, -1, v144
	v_readlane_b32 s72, v255, 0
	v_and_b32_e32 v145, 15, v144
	v_lshrrev_b32_e32 v146, 4, v144
	s_lshl_b32 s73, s72, 10
	v_lshlrev_b32_e32 v147, 3, v145
	v_lshl_add_u32 v148, v146, 7, v147
	v_lshlrev_b32_e32 v149, 3, v146
	v_lshl_add_u32 v150, v145, 9, v149
	v_add_u32_e32 v151, s73, v149
	v_mov_b32_e32 v152, 0
	v_mov_b32_e32 v153, 0
	v_mov_b32_e32 v154, 0
	v_mov_b32_e32 v155, 0
	v_mov_b32_e32 v156, 0
	v_mov_b32_e32 v157, 0
	v_mov_b32_e32 v158, 0
	v_mov_b32_e32 v159, 0
	ds_read_b64 v[160:161], v148 offset:8704
	ds_read_b64 v[162:163], v150 offset:16896
	ds_read_b64 v[164:165], v151 offset:0
	ds_read_b64 v[166:167], v151 offset:512
	ds_read_b64 v[168:169], v148 offset:9216
	ds_read_b64 v[170:171], v150 offset:16928
	ds_read_b64 v[172:173], v151 offset:32
	ds_read_b64 v[174:175], v151 offset:544
	ds_read_b64 v[176:177], v148 offset:9728
	ds_read_b64 v[178:179], v150 offset:16960
	ds_read_b64 v[180:181], v151 offset:64
	ds_read_b64 v[182:183], v151 offset:576
	ds_read_b64 v[184:185], v148 offset:10240
	ds_read_b64 v[186:187], v150 offset:16992
	ds_read_b64 v[188:189], v151 offset:96
	ds_read_b64 v[190:191], v151 offset:608
	s_waitcnt lgkmcnt(0)
	v_mul_f32_e32 v192, v163, v165
	v_mul_f32_e32 v193, v163, v164
	v_mul_f32_e32 v194, v163, v167
	v_mul_f32_e32 v195, v163, v166
	v_xor_b32_e32 v196, 0x80000000, v161
	v_fma_f32 v192, v162, v164, -v192
	v_fma_f32 v193, v162, v165, v193
	v_fma_f32 v194, v162, v166, -v194
	v_fma_f32 v195, v162, v167, v195
	s_nop 1
	v_mfma_f32_16x16x4_f32 v[152:155], v192, v160, v[152:155]
	v_mfma_f32_16x16x4_f32 v[156:159], v194, v160, v[156:159]
	v_mfma_f32_16x16x4_f32 v[152:155], v193, v196, v[152:155]
	v_mfma_f32_16x16x4_f32 v[156:159], v195, v196, v[156:159]
	v_mul_f32_e32 v200, v171, v173
	v_mul_f32_e32 v201, v171, v172
	v_mul_f32_e32 v202, v171, v175
	v_mul_f32_e32 v203, v171, v174
	v_xor_b32_e32 v204, 0x80000000, v169
	v_fma_f32 v200, v170, v172, -v200
	v_fma_f32 v201, v170, v173, v201
	v_fma_f32 v202, v170, v174, -v202
	v_fma_f32 v203, v170, v175, v203
	s_nop 1
	v_mfma_f32_16x16x4_f32 v[152:155], v200, v168, v[152:155]
	v_mfma_f32_16x16x4_f32 v[156:159], v202, v168, v[156:159]
	v_mfma_f32_16x16x4_f32 v[152:155], v201, v204, v[152:155]
	v_mfma_f32_16x16x4_f32 v[156:159], v203, v204, v[156:159]
	v_mul_f32_e32 v208, v179, v181
	v_mul_f32_e32 v209, v179, v180
	v_mul_f32_e32 v210, v179, v183
	v_mul_f32_e32 v211, v179, v182
	v_xor_b32_e32 v212, 0x80000000, v177
	v_fma_f32 v208, v178, v180, -v208
	v_fma_f32 v209, v178, v181, v209
	v_fma_f32 v210, v178, v182, -v210
	v_fma_f32 v211, v178, v183, v211
	s_nop 1
	v_mfma_f32_16x16x4_f32 v[152:155], v208, v176, v[152:155]
	v_mfma_f32_16x16x4_f32 v[156:159], v210, v176, v[156:159]
	v_mfma_f32_16x16x4_f32 v[152:155], v209, v212, v[152:155]
	v_mfma_f32_16x16x4_f32 v[156:159], v211, v212, v[156:159]
	v_mul_f32_e32 v216, v187, v189
	v_mul_f32_e32 v217, v187, v188
	v_mul_f32_e32 v218, v187, v191
	v_mul_f32_e32 v219, v187, v190
	v_xor_b32_e32 v220, 0x80000000, v185
	v_fma_f32 v216, v186, v188, -v216
	v_fma_f32 v217, v186, v189, v217
	v_fma_f32 v218, v186, v190, -v218
	v_fma_f32 v219, v186, v191, v219
	s_nop 1
	v_mfma_f32_16x16x4_f32 v[152:155], v216, v184, v[152:155]
	v_mfma_f32_16x16x4_f32 v[156:159], v218, v184, v[156:159]
	v_mfma_f32_16x16x4_f32 v[152:155], v217, v220, v[152:155]
	v_mfma_f32_16x16x4_f32 v[156:159], v219, v220, v[156:159]
	ds_read_b64 v[160:161], v148 offset:10752
	ds_read_b64 v[162:163], v150 offset:17024
	ds_read_b64 v[164:165], v151 offset:128
	ds_read_b64 v[166:167], v151 offset:640
	ds_read_b64 v[168:169], v148 offset:11264
	ds_read_b64 v[170:171], v150 offset:17056
	ds_read_b64 v[172:173], v151 offset:160
	ds_read_b64 v[174:175], v151 offset:672
	ds_read_b64 v[176:177], v148 offset:11776
	ds_read_b64 v[178:179], v150 offset:17088
	ds_read_b64 v[180:181], v151 offset:192
	ds_read_b64 v[182:183], v151 offset:704
	ds_read_b64 v[184:185], v148 offset:12288
	ds_read_b64 v[186:187], v150 offset:17120
	ds_read_b64 v[188:189], v151 offset:224
	ds_read_b64 v[190:191], v151 offset:736
	s_waitcnt lgkmcnt(0)
; __global__ void __launch_bounds__(NWAVES * 64, 2) fwd_kernel(Args args) {
;     ...
;             for (int idx = tid; idx < 4096; idx += 512) { const int j = idx >> 8, p = (idx >> 4) & 15, q = idx & 15; float sum = 0.f;
;                 for (int n = 0; n < 64; ++n) { const float cr = cc[(p * 64 + n) * 2], ci = cc[(p * 64 + n) * 2 + 1], ar = ap[(j * 64 + n) * 2], ai = ap[(j * 64 + n) * 2 + 1];
;                     const float tr = cr * ar - ci * ai, ti = cr * ai + ci * ar; sum += tr * bb[(n * 16 + q) * 2] - ti * bb[(n * 16 + q) * 2 + 1]; }
;                 if (j == 0 && p == q) sum += ssm_d[lg * 16 + p];
;                 kt[idx] = sum; }
	v_mul_f32_e32 v192, v163, v165
	v_mul_f32_e32 v193, v163, v164
	v_mul_f32_e32 v194, v163, v167
	v_mul_f32_e32 v195, v163, v166
	v_xor_b32_e32 v196, 0x80000000, v161
	v_fma_f32 v192, v162, v164, -v192
	v_fma_f32 v193, v162, v165, v193
	v_fma_f32 v194, v162, v166, -v194
	v_fma_f32 v195, v162, v167, v195
	s_nop 1
	v_mfma_f32_16x16x4_f32 v[152:155], v192, v160, v[152:155]
	v_mfma_f32_16x16x4_f32 v[156:159], v194, v160, v[156:159]
	v_mfma_f32_16x16x4_f32 v[152:155], v193, v196, v[152:155]
	v_mfma_f32_16x16x4_f32 v[156:159], v195, v196, v[156:159]
	v_mul_f32_e32 v200, v171, v173
	v_mul_f32_e32 v201, v171, v172
	v_mul_f32_e32 v202, v171, v175
	v_mul_f32_e32 v203, v171, v174
	v_xor_b32_e32 v204, 0x80000000, v169
	v_fma_f32 v200, v170, v172, -v200
	v_fma_f32 v201, v170, v173, v201
	v_fma_f32 v202, v170, v174, -v202
	v_fma_f32 v203, v170, v175, v203
	s_nop 1
	v_mfma_f32_16x16x4_f32 v[152:155], v200, v168, v[152:155]
	v_mfma_f32_16x16x4_f32 v[156:159], v202, v168, v[156:159]
	v_mfma_f32_16x16x4_f32 v[152:155], v201, v204, v[152:155]
	v_mfma_f32_16x16x4_f32 v[156:159], v203, v204, v[156:159]
	v_mul_f32_e32 v208, v179, v181
	v_mul_f32_e32 v209, v179, v180
	v_mul_f32_e32 v210, v179, v183
	v_mul_f32_e32 v211, v179, v182
	v_xor_b32_e32 v212, 0x80000000, v177
	v_fma_f32 v208, v178, v180, -v208
	v_fma_f32 v209, v178, v181, v209
	v_fma_f32 v210, v178, v182, -v210
	v_fma_f32 v211, v178, v183, v211
	s_nop 1
	v_mfma_f32_16x16x4_f32 v[152:155], v208, v176, v[152:155]
	v_mfma_f32_16x16x4_f32 v[156:159], v210, v176, v[156:159]
	v_mfma_f32_16x16x4_f32 v[152:155], v209, v212, v[152:155]
	v_mfma_f32_16x16x4_f32 v[156:159], v211, v212, v[156:159]
	v_mul_f32_e32 v216, v187, v189
	v_mul_f32_e32 v217, v187, v188
	v_mul_f32_e32 v218, v187, v191
	v_mul_f32_e32 v219, v187, v190
	v_xor_b32_e32 v220, 0x80000000, v185
	v_fma_f32 v216, v186, v188, -v216
	v_fma_f32 v217, v186, v189, v217
	v_fma_f32 v218, v186, v190, -v218
	v_fma_f32 v219, v186, v191, v219
	s_nop 1
	v_mfma_f32_16x16x4_f32 v[152:155], v216, v184, v[152:155]
	v_mfma_f32_16x16x4_f32 v[156:159], v218, v184, v[156:159]
	v_mfma_f32_16x16x4_f32 v[152:155], v217, v220, v[152:155]
	v_mfma_f32_16x16x4_f32 v[156:159], v219, v220, v[156:159]
	ds_read_b64 v[160:161], v148 offset:12800
	ds_read_b64 v[162:163], v150 offset:17152
	ds_read_b64 v[164:165], v151 offset:256
	ds_read_b64 v[166:167], v151 offset:768
	ds_read_b64 v[168:169], v148 offset:13312
	ds_read_b64 v[170:171], v150 offset:17184
	ds_read_b64 v[172:173], v151 offset:288
	ds_read_b64 v[174:175], v151 offset:800
	ds_read_b64 v[176:177], v148 offset:13824
	ds_read_b64 v[178:179], v150 offset:17216
	ds_read_b64 v[180:181], v151 offset:320
	ds_read_b64 v[182:183], v151 offset:832
	ds_read_b64 v[184:185], v148 offset:14336
	ds_read_b64 v[186:187], v150 offset:17248
	ds_read_b64 v[188:189], v151 offset:352
	ds_read_b64 v[190:191], v151 offset:864
	s_waitcnt lgkmcnt(0)
	v_mul_f32_e32 v192, v163, v165
	v_mul_f32_e32 v193, v163, v164
	v_mul_f32_e32 v194, v163, v167
	v_mul_f32_e32 v195, v163, v166
	v_xor_b32_e32 v196, 0x80000000, v161
	v_fma_f32 v192, v162, v164, -v192
	v_fma_f32 v193, v162, v165, v193
	v_fma_f32 v194, v162, v166, -v194
	v_fma_f32 v195, v162, v167, v195
	s_nop 1
	v_mfma_f32_16x16x4_f32 v[152:155], v192, v160, v[152:155]
	v_mfma_f32_16x16x4_f32 v[156:159], v194, v160, v[156:159]
	v_mfma_f32_16x16x4_f32 v[152:155], v193, v196, v[152:155]
	v_mfma_f32_16x16x4_f32 v[156:159], v195, v196, v[156:159]
	v_mul_f32_e32 v200, v171, v173
	v_mul_f32_e32 v201, v171, v172
	v_mul_f32_e32 v202, v171, v175
	v_mul_f32_e32 v203, v171, v174
	v_xor_b32_e32 v204, 0x80000000, v169
	v_fma_f32 v200, v170, v172, -v200
	v_fma_f32 v201, v170, v173, v201
	v_fma_f32 v202, v170, v174, -v202
	v_fma_f32 v203, v170, v175, v203
	s_nop 1
	v_mfma_f32_16x16x4_f32 v[152:155], v200, v168, v[152:155]
	v_mfma_f32_16x16x4_f32 v[156:159], v202, v168, v[156:159]
	v_mfma_f32_16x16x4_f32 v[152:155], v201, v204, v[152:155]
	v_mfma_f32_16x16x4_f32 v[156:159], v203, v204, v[156:159]
	v_mul_f32_e32 v208, v179, v181
	v_mul_f32_e32 v209, v179, v180
	v_mul_f32_e32 v210, v179, v183
	v_mul_f32_e32 v211, v179, v182
	v_xor_b32_e32 v212, 0x80000000, v177
	v_fma_f32 v208, v178, v180, -v208
	v_fma_f32 v209, v178, v181, v209
	v_fma_f32 v210, v178, v182, -v210
	v_fma_f32 v211, v178, v183, v211
	s_nop 1
	v_mfma_f32_16x16x4_f32 v[152:155], v208, v176, v[152:155]
	v_mfma_f32_16x16x4_f32 v[156:159], v210, v176, v[156:159]
	v_mfma_f32_16x16x4_f32 v[152:155], v209, v212, v[152:155]
	v_mfma_f32_16x16x4_f32 v[156:159], v211, v212, v[156:159]
	v_mul_f32_e32 v216, v187, v189
	v_mul_f32_e32 v217, v187, v188
	v_mul_f32_e32 v218, v187, v191
	v_mul_f32_e32 v219, v187, v190
	v_xor_b32_e32 v220, 0x80000000, v185
	v_fma_f32 v216, v186, v188, -v216
	v_fma_f32 v217, v186, v189, v217
	v_fma_f32 v218, v186, v190, -v218
	v_fma_f32 v219, v186, v191, v219
	s_nop 1
	v_mfma_f32_16x16x4_f32 v[152:155], v216, v184, v[152:155]
	v_mfma_f32_16x16x4_f32 v[156:159], v218, v184, v[156:159]
	v_mfma_f32_16x16x4_f32 v[152:155], v217, v220, v[152:155]
	v_mfma_f32_16x16x4_f32 v[156:159], v219, v220, v[156:159]
	ds_read_b64 v[160:161], v148 offset:14848
	ds_read_b64 v[162:163], v150 offset:17280
	ds_read_b64 v[164:165], v151 offset:384
	ds_read_b64 v[166:167], v151 offset:896
	ds_read_b64 v[168:169], v148 offset:15360
	ds_read_b64 v[170:171], v150 offset:17312
	ds_read_b64 v[172:173], v151 offset:416
	ds_read_b64 v[174:175], v151 offset:928
	ds_read_b64 v[176:177], v148 offset:15872
	ds_read_b64 v[178:179], v150 offset:17344
	ds_read_b64 v[180:181], v151 offset:448
	ds_read_b64 v[182:183], v151 offset:960
	ds_read_b64 v[184:185], v148 offset:16384
	ds_read_b64 v[186:187], v150 offset:17376
	ds_read_b64 v[188:189], v151 offset:480
	ds_read_b64 v[190:191], v151 offset:992
	s_waitcnt lgkmcnt(0)
; __device__ __forceinline__ unsigned pk2(float lo, float hi) { return f2bf(lo) | (f2bf(hi) << 16); }
; __global__ void __launch_bounds__(NWAVES * 64, 2) fwd_kernel(Args args) {
;     ...
;             for (int idx = tid; idx < 4096; idx += 512) { const int j = idx >> 8, p = (idx >> 4) & 15, q = idx & 15; float sum = 0.f;
;                 for (int n = 0; n < 64; ++n) { const float cr = cc[(p * 64 + n) * 2], ci = cc[(p * 64 + n) * 2 + 1], ar = ap[(j * 64 + n) * 2], ai = ap[(j * 64 + n) * 2 + 1];
;                     const float tr = cr * ar - ci * ai, ti = cr * ai + ci * ar; sum += tr * bb[(n * 16 + q) * 2] - ti * bb[(n * 16 + q) * 2 + 1]; }
;                 if (j == 0 && p == q) sum += ssm_d[lg * 16 + p];
;                 kt[idx] = sum; }
;             __syncthreads();
;             bf16* W1 = (bf16*)(ws + WS_S5W + (size_t)l * S5W_LAYER) + (size_t)g * 128 * 256;
;             bf16* W2 = (bf16*)(ws + WS_S5W + (size_t)l * S5W_LAYER + S5W2_OFF) + (size_t)g * 256 * 384;
;             for (int i2 = tid; i2 < 256 * 192; i2 += 512) { const int row = i2 / 192, c0 = (i2 % 192) * 2, t = row >> 4, p = row & 15; float v[2];
; #pragma unroll
;                 for (int e = 0; e < 2; ++e) { const int col = c0 + e;
;                     if (col < 256) { const int tau = col >> 4, q = col & 15; v[e] = (tau <= t) ? kt[((t - tau) << 8) + (p << 4) + q] : 0.f; }
;                     else { const int n = (col - 256) & 63; const float cr = cc[(p * 64 + n) * 2], ci = cc[(p * 64 + n) * 2 + 1], ar = ap[((t + 1) * 64 + n) * 2], ai = ap[((t + 1) * 64 + n) * 2 + 1];
;                         v[e] = (col < 320) ? (cr * ar - ci * ai) : -(cr * ai + ci * ar); } }
;                 *(unsigned*)(W2 + (size_t)row * 384 + c0) = pk2(v[0], v[1]); }
	v_mul_f32_e32 v192, v163, v165
	v_mul_f32_e32 v193, v163, v164
	v_mul_f32_e32 v194, v163, v167
	v_mul_f32_e32 v195, v163, v166
	v_xor_b32_e32 v196, 0x80000000, v161
	v_fma_f32 v192, v162, v164, -v192
	v_fma_f32 v193, v162, v165, v193
	v_fma_f32 v194, v162, v166, -v194
	v_fma_f32 v195, v162, v167, v195
	s_nop 1
	v_mfma_f32_16x16x4_f32 v[152:155], v192, v160, v[152:155]
	v_mfma_f32_16x16x4_f32 v[156:159], v194, v160, v[156:159]
	v_mfma_f32_16x16x4_f32 v[152:155], v193, v196, v[152:155]
	v_mfma_f32_16x16x4_f32 v[156:159], v195, v196, v[156:159]
	v_mul_f32_e32 v200, v171, v173
	v_mul_f32_e32 v201, v171, v172
	v_mul_f32_e32 v202, v171, v175
	v_mul_f32_e32 v203, v171, v174
	v_xor_b32_e32 v204, 0x80000000, v169
	v_fma_f32 v200, v170, v172, -v200
	v_fma_f32 v201, v170, v173, v201
	v_fma_f32 v202, v170, v174, -v202
	v_fma_f32 v203, v170, v175, v203
	s_nop 1
	v_mfma_f32_16x16x4_f32 v[152:155], v200, v168, v[152:155]
	v_mfma_f32_16x16x4_f32 v[156:159], v202, v168, v[156:159]
	v_mfma_f32_16x16x4_f32 v[152:155], v201, v204, v[152:155]
	v_mfma_f32_16x16x4_f32 v[156:159], v203, v204, v[156:159]
	v_mul_f32_e32 v208, v179, v181
	v_mul_f32_e32 v209, v179, v180
	v_mul_f32_e32 v210, v179, v183
	v_mul_f32_e32 v211, v179, v182
	v_xor_b32_e32 v212, 0x80000000, v177
	v_fma_f32 v208, v178, v180, -v208
	v_fma_f32 v209, v178, v181, v209
	v_fma_f32 v210, v178, v182, -v210
	v_fma_f32 v211, v178, v183, v211
	s_nop 1
	v_mfma_f32_16x16x4_f32 v[152:155], v208, v176, v[152:155]
	v_mfma_f32_16x16x4_f32 v[156:159], v210, v176, v[156:159]
	v_mfma_f32_16x16x4_f32 v[152:155], v209, v212, v[152:155]
	v_mfma_f32_16x16x4_f32 v[156:159], v211, v212, v[156:159]
	v_mul_f32_e32 v216, v187, v189
	v_mul_f32_e32 v217, v187, v188
	v_mul_f32_e32 v218, v187, v191
	v_mul_f32_e32 v219, v187, v190
	v_xor_b32_e32 v220, 0x80000000, v185
	v_fma_f32 v216, v186, v188, -v216
	v_fma_f32 v217, v186, v189, v217
	v_fma_f32 v218, v186, v190, -v218
	v_fma_f32 v219, v186, v191, v219
	s_nop 1
	v_mfma_f32_16x16x4_f32 v[152:155], v216, v184, v[152:155]
	v_mfma_f32_16x16x4_f32 v[156:159], v218, v184, v[156:159]
	v_mfma_f32_16x16x4_f32 v[152:155], v217, v220, v[152:155]
	v_mfma_f32_16x16x4_f32 v[156:159], v219, v220, v[156:159]
	s_cmp_eq_u32 s72, 0
	s_cselect_b32 s74, 1.0, 0
	v_add_u32_e32 v200, s25, v145
	v_lshlrev_b32_e32 v200, 2, v200
	global_load_dword v201, v200, s[40:41]
	v_lshlrev_b32_e32 v203, 2, v146
	v_sub_u32_e32 v202, v145, v203
	s_lshl_b32 s75, s72, 11
	v_lshlrev_b32_e32 v205, 2, v145
	v_lshl_add_u32 v205, v146, 8, v205
	v_add_u32_e32 v205, s75, v205
	s_waitcnt vmcnt(0)
	v_mul_f32_e32 v201, s74, v201
	s_nop 15
	v_cmp_eq_u32_e32 vcc, 0, v202
	s_nop 1
	v_cndmask_b32_e32 v204, 0, v201, vcc
	v_add_f32_e32 v152, v152, v204
	v_cmp_eq_u32_e32 vcc, 1, v202
	s_nop 1
	v_cndmask_b32_e32 v204, 0, v201, vcc
	v_add_f32_e32 v153, v153, v204
	v_cmp_eq_u32_e32 vcc, 2, v202
	s_nop 1
	v_cndmask_b32_e32 v204, 0, v201, vcc
	v_add_f32_e32 v154, v154, v204
	v_cmp_eq_u32_e32 vcc, 3, v202
	s_nop 1
	v_cndmask_b32_e32 v204, 0, v201, vcc
	v_add_f32_e32 v155, v155, v204
	ds_write_b32 v205, v152 offset:25088
	ds_write_b32 v205, v156 offset:26112
	ds_write_b32 v205, v153 offset:25152
	ds_write_b32 v205, v157 offset:26176
	ds_write_b32 v205, v154 offset:25216
	ds_write_b32 v205, v158 offset:26240
	ds_write_b32 v205, v155 offset:25280
	ds_write_b32 v205, v159 offset:26304
.LBB0_42:
	s_or_b64 exec, exec, s[0:1]
	s_ashr_i32 s0, s24, 6
	s_ashr_i32 s1, s0, 31
	s_and_b32 s25, s24, 63
	s_lshl_b64 s[26:27], s[0:1], 24
	s_add_u32 s0, s11, s26
	s_addc_u32 s1, s33, s27
	s_mul_i32 s25, s25, 0x30000
	s_add_u32 s0, s0, s25
	s_addc_u32 s1, s1, 0
	s_add_u32 s28, s0, 0x400000
	s_addc_u32 s29, s1, 0
	s_mov_b64 s[36:37], 0
	v_mov_b32_e32 v14, v38
	s_waitcnt lgkmcnt(0)
	s_barrier
	v_and_b32_e32 v144, 31, v38
	v_lshrrev_b32_e32 v145, 5, v38
	v_lshrrev_b32_e32 v146, 1, v144
	v_and_b32_e32 v147, 1, v144
	v_lshlrev_b32_e32 v147, 5, v147
	v_lshl_add_u32 v148, v145, 6, v147
	v_mul_u32_u24_e32 v149, 0x300, v145
	v_lshl_add_u32 v149, v144, 4, v149
	s_mov_b64 s[74:75], s[28:29]
	v_sub_u32_e32 v150, 0, v146
	v_cmp_ge_u32_e64 s[76:77], 0, v146
	v_max_i32_e32 v150, 0, v150
	v_lshl_add_u32 v151, v150, 10, v148
	ds_read_b128 v[152:155], v151 offset:25088
	ds_read_b128 v[156:159], v151 offset:25104
	v_sub_u32_e32 v150, 1, v146
	v_cmp_ge_u32_e64 s[78:79], 1, v146
	v_max_i32_e32 v150, 0, v150
	v_lshl_add_u32 v151, v150, 10, v148
	ds_read_b128 v[160:163], v151 offset:25088
	ds_read_b128 v[164:167], v151 offset:25104
	v_sub_u32_e32 v150, 2, v146
	v_cmp_ge_u32_e64 s[80:81], 2, v146
	v_max_i32_e32 v150, 0, v150
	v_lshl_add_u32 v151, v150, 10, v148
	ds_read_b128 v[168:171], v151 offset:25088
	ds_read_b128 v[172:175], v151 offset:25104
	v_sub_u32_e32 v150, 3, v146
	v_cmp_ge_u32_e64 s[82:83], 3, v146
	v_max_i32_e32 v150, 0, v150
	v_lshl_add_u32 v151, v150, 10, v148
	ds_read_b128 v[176:179], v151 offset:25088
	ds_read_b128 v[180:183], v151 offset:25104
	s_waitcnt lgkmcnt(0)
; __device__ __forceinline__ unsigned pk2(float lo, float hi) { return f2bf(lo) | (f2bf(hi) << 16); }
; __global__ void __launch_bounds__(NWAVES * 64, 2) fwd_kernel(Args args) {
;     ...
;             for (int i2 = tid; i2 < 256 * 192; i2 += 512) { const int row = i2 / 192, c0 = (i2 % 192) * 2, t = row >> 4, p = row & 15; float v[2];
; #pragma unroll
;                 for (int e = 0; e < 2; ++e) { const int col = c0 + e;
;                     if (col < 256) { const int tau = col >> 4, q = col & 15; v[e] = (tau <= t) ? kt[((t - tau) << 8) + (p << 4) + q] : 0.f; }
;                     else { const int n = (col - 256) & 63; const float cr = cc[(p * 64 + n) * 2], ci = cc[(p * 64 + n) * 2 + 1], ar = ap[((t + 1) * 64 + n) * 2], ai = ap[((t + 1) * 64 + n) * 2 + 1];
;                         v[e] = (col < 320) ? (cr * ar - ci * ai) : -(cr * ai + ci * ar); } }
;                 *(unsigned*)(W2 + (size_t)row * 384 + c0) = pk2(v[0], v[1]); }
	v_cvt_pk_bf16_f32 v184, v152, v153
	v_cvt_pk_bf16_f32 v185, v154, v155
	v_cvt_pk_bf16_f32 v186, v156, v157
	v_cvt_pk_bf16_f32 v187, v158, v159
	v_cndmask_b32_e64 v184, 0, v184, s[76:77]
	v_cndmask_b32_e64 v185, 0, v185, s[76:77]
	v_cndmask_b32_e64 v186, 0, v186, s[76:77]
	v_cndmask_b32_e64 v187, 0, v187, s[76:77]
	global_store_dwordx4 v149, v[184:187], s[74:75]
	s_add_u32 s74, s74, 0x3000
	s_addc_u32 s75, s75, 0
	v_cvt_pk_bf16_f32 v188, v160, v161
	v_cvt_pk_bf16_f32 v189, v162, v163
	v_cvt_pk_bf16_f32 v190, v164, v165
	v_cvt_pk_bf16_f32 v191, v166, v167
	v_cndmask_b32_e64 v188, 0, v188, s[78:79]
	v_cndmask_b32_e64 v189, 0, v189, s[78:79]
	v_cndmask_b32_e64 v190, 0, v190, s[78:79]
	v_cndmask_b32_e64 v191, 0, v191, s[78:79]
	global_store_dwordx4 v149, v[188:191], s[74:75]
	s_add_u32 s74, s74, 0x3000
	s_addc_u32 s75, s75, 0
	v_cvt_pk_bf16_f32 v192, v168, v169
	v_cvt_pk_bf16_f32 v193, v170, v171
	v_cvt_pk_bf16_f32 v194, v172, v173
	v_cvt_pk_bf16_f32 v195, v174, v175
	v_cndmask_b32_e64 v192, 0, v192, s[80:81]
	v_cndmask_b32_e64 v193, 0, v193, s[80:81]
	v_cndmask_b32_e64 v194, 0, v194, s[80:81]
	v_cndmask_b32_e64 v195, 0, v195, s[80:81]
	global_store_dwordx4 v149, v[192:195], s[74:75]
	s_add_u32 s74, s74, 0x3000
	s_addc_u32 s75, s75, 0
	v_cvt_pk_bf16_f32 v196, v176, v177
	v_cvt_pk_bf16_f32 v197, v178, v179
	v_cvt_pk_bf16_f32 v198, v180, v181
	v_cvt_pk_bf16_f32 v199, v182, v183
	v_cndmask_b32_e64 v196, 0, v196, s[82:83]
	v_cndmask_b32_e64 v197, 0, v197, s[82:83]
	v_cndmask_b32_e64 v198, 0, v198, s[82:83]
	v_cndmask_b32_e64 v199, 0, v199, s[82:83]
	global_store_dwordx4 v149, v[196:199], s[74:75]
	s_add_u32 s74, s74, 0x3000
	s_addc_u32 s75, s75, 0
	v_sub_u32_e32 v150, 4, v146
	v_cmp_ge_u32_e64 s[76:77], 4, v146
	v_max_i32_e32 v150, 0, v150
	v_lshl_add_u32 v151, v150, 10, v148
	ds_read_b128 v[152:155], v151 offset:25088
	ds_read_b128 v[156:159], v151 offset:25104
	v_sub_u32_e32 v150, 5, v146
	v_cmp_ge_u32_e64 s[78:79], 5, v146
	v_max_i32_e32 v150, 0, v150
	v_lshl_add_u32 v151, v150, 10, v148
	ds_read_b128 v[160:163], v151 offset:25088
	ds_read_b128 v[164:167], v151 offset:25104
	v_sub_u32_e32 v150, 6, v146
	v_cmp_ge_u32_e64 s[80:81], 6, v146
	v_max_i32_e32 v150, 0, v150
	v_lshl_add_u32 v151, v150, 10, v148
	ds_read_b128 v[168:171], v151 offset:25088
	ds_read_b128 v[172:175], v151 offset:25104
	v_sub_u32_e32 v150, 7, v146
	v_cmp_ge_u32_e64 s[82:83], 7, v146
	v_max_i32_e32 v150, 0, v150
	v_lshl_add_u32 v151, v150, 10, v148
	ds_read_b128 v[176:179], v151 offset:25088
	ds_read_b128 v[180:183], v151 offset:25104
	s_waitcnt lgkmcnt(0)
	v_cvt_pk_bf16_f32 v184, v152, v153
	v_cvt_pk_bf16_f32 v185, v154, v155
	v_cvt_pk_bf16_f32 v186, v156, v157
	v_cvt_pk_bf16_f32 v187, v158, v159
	v_cndmask_b32_e64 v184, 0, v184, s[76:77]
	v_cndmask_b32_e64 v185, 0, v185, s[76:77]
	v_cndmask_b32_e64 v186, 0, v186, s[76:77]
	v_cndmask_b32_e64 v187, 0, v187, s[76:77]
	global_store_dwordx4 v149, v[184:187], s[74:75]
	s_add_u32 s74, s74, 0x3000
	s_addc_u32 s75, s75, 0
	v_cvt_pk_bf16_f32 v188, v160, v161
	v_cvt_pk_bf16_f32 v189, v162, v163
	v_cvt_pk_bf16_f32 v190, v164, v165
	v_cvt_pk_bf16_f32 v191, v166, v167
	v_cndmask_b32_e64 v188, 0, v188, s[78:79]
	v_cndmask_b32_e64 v189, 0, v189, s[78:79]
	v_cndmask_b32_e64 v190, 0, v190, s[78:79]
	v_cndmask_b32_e64 v191, 0, v191, s[78:79]
	global_store_dwordx4 v149, v[188:191], s[74:75]
	s_add_u32 s74, s74, 0x3000
	s_addc_u32 s75, s75, 0
	v_cvt_pk_bf16_f32 v192, v168, v169
	v_cvt_pk_bf16_f32 v193, v170, v171
	v_cvt_pk_bf16_f32 v194, v172, v173
	v_cvt_pk_bf16_f32 v195, v174, v175
	v_cndmask_b32_e64 v192, 0, v192, s[80:81]
	v_cndmask_b32_e64 v193, 0, v193, s[80:81]
	v_cndmask_b32_e64 v194, 0, v194, s[80:81]
	v_cndmask_b32_e64 v195, 0, v195, s[80:81]
	global_store_dwordx4 v149, v[192:195], s[74:75]
	s_add_u32 s74, s74, 0x3000
	s_addc_u32 s75, s75, 0
	v_cvt_pk_bf16_f32 v196, v176, v177
	v_cvt_pk_bf16_f32 v197, v178, v179
	v_cvt_pk_bf16_f32 v198, v180, v181
	v_cvt_pk_bf16_f32 v199, v182, v183
	v_cndmask_b32_e64 v196, 0, v196, s[82:83]
	v_cndmask_b32_e64 v197, 0, v197, s[82:83]
	v_cndmask_b32_e64 v198, 0, v198, s[82:83]
	v_cndmask_b32_e64 v199, 0, v199, s[82:83]
	global_store_dwordx4 v149, v[196:199], s[74:75]
	s_add_u32 s74, s74, 0x3000
	s_addc_u32 s75, s75, 0
	v_sub_u32_e32 v150, 8, v146
	v_cmp_ge_u32_e64 s[76:77], 8, v146
	v_max_i32_e32 v150, 0, v150
	v_lshl_add_u32 v151, v150, 10, v148
	ds_read_b128 v[152:155], v151 offset:25088
	ds_read_b128 v[156:159], v151 offset:25104
	v_sub_u32_e32 v150, 9, v146
	v_cmp_ge_u32_e64 s[78:79], 9, v146
	v_max_i32_e32 v150, 0, v150
	v_lshl_add_u32 v151, v150, 10, v148
	ds_read_b128 v[160:163], v151 offset:25088
	ds_read_b128 v[164:167], v151 offset:25104
	v_sub_u32_e32 v150, 10, v146
	v_cmp_ge_u32_e64 s[80:81], 10, v146
	v_max_i32_e32 v150, 0, v150
	v_lshl_add_u32 v151, v150, 10, v148
	ds_read_b128 v[168:171], v151 offset:25088
	ds_read_b128 v[172:175], v151 offset:25104
	v_sub_u32_e32 v150, 11, v146
	v_cmp_ge_u32_e64 s[82:83], 11, v146
	v_max_i32_e32 v150, 0, v150
	v_lshl_add_u32 v151, v150, 10, v148
	ds_read_b128 v[176:179], v151 offset:25088
	ds_read_b128 v[180:183], v151 offset:25104
	s_waitcnt lgkmcnt(0)
; __device__ __forceinline__ unsigned pk2(float lo, float hi) { return f2bf(lo) | (f2bf(hi) << 16); }
; __global__ void __launch_bounds__(NWAVES * 64, 2) fwd_kernel(Args args) {
;     ...
;             for (int i2 = tid; i2 < 256 * 192; i2 += 512) { const int row = i2 / 192, c0 = (i2 % 192) * 2, t = row >> 4, p = row & 15; float v[2];
; #pragma unroll
;                 for (int e = 0; e < 2; ++e) { const int col = c0 + e;
;                     if (col < 256) { const int tau = col >> 4, q = col & 15; v[e] = (tau <= t) ? kt[((t - tau) << 8) + (p << 4) + q] : 0.f; }
;                     else { const int n = (col - 256) & 63; const float cr = cc[(p * 64 + n) * 2], ci = cc[(p * 64 + n) * 2 + 1], ar = ap[((t + 1) * 64 + n) * 2], ai = ap[((t + 1) * 64 + n) * 2 + 1];
;                         v[e] = (col < 320) ? (cr * ar - ci * ai) : -(cr * ai + ci * ar); } }
;                 *(unsigned*)(W2 + (size_t)row * 384 + c0) = pk2(v[0], v[1]); }
	v_cvt_pk_bf16_f32 v184, v152, v153
	v_cvt_pk_bf16_f32 v185, v154, v155
	v_cvt_pk_bf16_f32 v186, v156, v157
	v_cvt_pk_bf16_f32 v187, v158, v159
	v_cndmask_b32_e64 v184, 0, v184, s[76:77]
	v_cndmask_b32_e64 v185, 0, v185, s[76:77]
	v_cndmask_b32_e64 v186, 0, v186, s[76:77]
	v_cndmask_b32_e64 v187, 0, v187, s[76:77]
	global_store_dwordx4 v149, v[184:187], s[74:75]
	s_add_u32 s74, s74, 0x3000
	s_addc_u32 s75, s75, 0
	v_cvt_pk_bf16_f32 v188, v160, v161
	v_cvt_pk_bf16_f32 v189, v162, v163
	v_cvt_pk_bf16_f32 v190, v164, v165
	v_cvt_pk_bf16_f32 v191, v166, v167
	v_cndmask_b32_e64 v188, 0, v188, s[78:79]
	v_cndmask_b32_e64 v189, 0, v189, s[78:79]
	v_cndmask_b32_e64 v190, 0, v190, s[78:79]
	v_cndmask_b32_e64 v191, 0, v191, s[78:79]
	global_store_dwordx4 v149, v[188:191], s[74:75]
	s_add_u32 s74, s74, 0x3000
	s_addc_u32 s75, s75, 0
	v_cvt_pk_bf16_f32 v192, v168, v169
	v_cvt_pk_bf16_f32 v193, v170, v171
	v_cvt_pk_bf16_f32 v194, v172, v173
	v_cvt_pk_bf16_f32 v195, v174, v175
	v_cndmask_b32_e64 v192, 0, v192, s[80:81]
	v_cndmask_b32_e64 v193, 0, v193, s[80:81]
	v_cndmask_b32_e64 v194, 0, v194, s[80:81]
	v_cndmask_b32_e64 v195, 0, v195, s[80:81]
	global_store_dwordx4 v149, v[192:195], s[74:75]
	s_add_u32 s74, s74, 0x3000
	s_addc_u32 s75, s75, 0
	v_cvt_pk_bf16_f32 v196, v176, v177
	v_cvt_pk_bf16_f32 v197, v178, v179
	v_cvt_pk_bf16_f32 v198, v180, v181
	v_cvt_pk_bf16_f32 v199, v182, v183
	v_cndmask_b32_e64 v196, 0, v196, s[82:83]
	v_cndmask_b32_e64 v197, 0, v197, s[82:83]
	v_cndmask_b32_e64 v198, 0, v198, s[82:83]
	v_cndmask_b32_e64 v199, 0, v199, s[82:83]
	global_store_dwordx4 v149, v[196:199], s[74:75]
	s_add_u32 s74, s74, 0x3000
	s_addc_u32 s75, s75, 0
	v_sub_u32_e32 v150, 12, v146
	v_cmp_ge_u32_e64 s[76:77], 12, v146
	v_max_i32_e32 v150, 0, v150
	v_lshl_add_u32 v151, v150, 10, v148
	ds_read_b128 v[152:155], v151 offset:25088
	ds_read_b128 v[156:159], v151 offset:25104
	v_sub_u32_e32 v150, 13, v146
	v_cmp_ge_u32_e64 s[78:79], 13, v146
	v_max_i32_e32 v150, 0, v150
	v_lshl_add_u32 v151, v150, 10, v148
	ds_read_b128 v[160:163], v151 offset:25088
	ds_read_b128 v[164:167], v151 offset:25104
	v_sub_u32_e32 v150, 14, v146
	v_cmp_ge_u32_e64 s[80:81], 14, v146
	v_max_i32_e32 v150, 0, v150
	v_lshl_add_u32 v151, v150, 10, v148
	ds_read_b128 v[168:171], v151 offset:25088
	ds_read_b128 v[172:175], v151 offset:25104
	v_sub_u32_e32 v150, 15, v146
	v_cmp_ge_u32_e64 s[82:83], 15, v146
	v_max_i32_e32 v150, 0, v150
	v_lshl_add_u32 v151, v150, 10, v148
	ds_read_b128 v[176:179], v151 offset:25088
	ds_read_b128 v[180:183], v151 offset:25104
	s_waitcnt lgkmcnt(0)
	v_cvt_pk_bf16_f32 v184, v152, v153
	v_cvt_pk_bf16_f32 v185, v154, v155
	v_cvt_pk_bf16_f32 v186, v156, v157
	v_cvt_pk_bf16_f32 v187, v158, v159
	v_cndmask_b32_e64 v184, 0, v184, s[76:77]
	v_cndmask_b32_e64 v185, 0, v185, s[76:77]
	v_cndmask_b32_e64 v186, 0, v186, s[76:77]
	v_cndmask_b32_e64 v187, 0, v187, s[76:77]
	global_store_dwordx4 v149, v[184:187], s[74:75]
	s_add_u32 s74, s74, 0x3000
	s_addc_u32 s75, s75, 0
	v_cvt_pk_bf16_f32 v188, v160, v161
	v_cvt_pk_bf16_f32 v189, v162, v163
	v_cvt_pk_bf16_f32 v190, v164, v165
	v_cvt_pk_bf16_f32 v191, v166, v167
	v_cndmask_b32_e64 v188, 0, v188, s[78:79]
	v_cndmask_b32_e64 v189, 0, v189, s[78:79]
	v_cndmask_b32_e64 v190, 0, v190, s[78:79]
	v_cndmask_b32_e64 v191, 0, v191, s[78:79]
	global_store_dwordx4 v149, v[188:191], s[74:75]
	s_add_u32 s74, s74, 0x3000
	s_addc_u32 s75, s75, 0
	v_cvt_pk_bf16_f32 v192, v168, v169
	v_cvt_pk_bf16_f32 v193, v170, v171
	v_cvt_pk_bf16_f32 v194, v172, v173
	v_cvt_pk_bf16_f32 v195, v174, v175
	v_cndmask_b32_e64 v192, 0, v192, s[80:81]
	v_cndmask_b32_e64 v193, 0, v193, s[80:81]
	v_cndmask_b32_e64 v194, 0, v194, s[80:81]
	v_cndmask_b32_e64 v195, 0, v195, s[80:81]
	global_store_dwordx4 v149, v[192:195], s[74:75]
	s_add_u32 s74, s74, 0x3000
	s_addc_u32 s75, s75, 0
	v_cvt_pk_bf16_f32 v196, v176, v177
	v_cvt_pk_bf16_f32 v197, v178, v179
	v_cvt_pk_bf16_f32 v198, v180, v181
	v_cvt_pk_bf16_f32 v199, v182, v183
	v_cndmask_b32_e64 v196, 0, v196, s[82:83]
	v_cndmask_b32_e64 v197, 0, v197, s[82:83]
	v_cndmask_b32_e64 v198, 0, v198, s[82:83]
	v_cndmask_b32_e64 v199, 0, v199, s[82:83]
	global_store_dwordx4 v149, v[196:199], s[74:75]
	s_add_u32 s74, s74, 0x3000
	s_addc_u32 s75, s75, 0
	v_and_b32_e32 v144, 15, v38
	v_lshrrev_b32_e32 v145, 4, v38
	v_and_b32_e32 v146, 15, v145
	v_lshrrev_b32_e32 v147, 4, v145
	v_and_b32_e32 v148, 7, v144
	v_cmp_lt_u32_e64 s[76:77], 7, v144
	v_lshlrev_b32_e32 v149, 6, v148
	v_lshl_add_u32 v150, v146, 9, v149
	ds_read_b128 v[152:155], v150 offset:16896
	ds_read_b128 v[156:159], v150 offset:16912
	ds_read_b128 v[160:163], v150 offset:16928
	ds_read_b128 v[164:167], v150 offset:16944
	v_add_u32_e32 v151, 1, v147
	v_lshl_add_u32 v151, v151, 9, v149
	v_mul_u32_u24_e32 v168, 0x300, v145
	v_lshl_add_u32 v168, v144, 4, v168
	v_add_u32_e32 v168, 0x200, v168
	s_mov_b64 s[74:75], s[28:29]
	ds_read_b128 v[170:173], v151 offset:0
	ds_read_b128 v[174:177], v151 offset:16
	ds_read_b128 v[178:181], v151 offset:32
	ds_read_b128 v[182:185], v151 offset:48
	s_waitcnt lgkmcnt(0)
; __device__ __forceinline__ unsigned pk2(float lo, float hi) { return f2bf(lo) | (f2bf(hi) << 16); }
; __global__ void __launch_bounds__(NWAVES * 64, 2) fwd_kernel(Args args) {
;     ...
;                     else { const int n = (col - 256) & 63; const float cr = cc[(p * 64 + n) * 2], ci = cc[(p * 64 + n) * 2 + 1], ar = ap[((t + 1) * 64 + n) * 2], ai = ap[((t + 1) * 64 + n) * 2 + 1];
;                         v[e] = (col < 320) ? (cr * ar - ci * ai) : -(cr * ai + ci * ar); } }
;                 *(unsigned*)(W2 + (size_t)row * 384 + c0) = pk2(v[0], v[1]); }
	v_mul_f32_e32 v190, v152, v170
	v_mul_f32_e32 v191, v153, v171
	v_mul_f32_e32 v192, v152, v171
	v_mul_f32_e32 v193, v153, v170
	v_sub_f32_e32 v190, v190, v191
	v_add_f32_e32 v192, v192, v193
	v_cndmask_b32_e64 v200, v190, -v192, s[76:77]
	v_mul_f32_e32 v194, v154, v172
	v_mul_f32_e32 v195, v155, v173
	v_mul_f32_e32 v196, v154, v173
	v_mul_f32_e32 v197, v155, v172
	v_sub_f32_e32 v194, v194, v195
	v_add_f32_e32 v196, v196, v197
	v_cndmask_b32_e64 v201, v194, -v196, s[76:77]
	v_mul_f32_e32 v190, v156, v174
	v_mul_f32_e32 v191, v157, v175
	v_mul_f32_e32 v192, v156, v175
	v_mul_f32_e32 v193, v157, v174
	v_sub_f32_e32 v190, v190, v191
	v_add_f32_e32 v192, v192, v193
	v_cndmask_b32_e64 v202, v190, -v192, s[76:77]
	v_mul_f32_e32 v194, v158, v176
	v_mul_f32_e32 v195, v159, v177
	v_mul_f32_e32 v196, v158, v177
	v_mul_f32_e32 v197, v159, v176
	v_sub_f32_e32 v194, v194, v195
	v_add_f32_e32 v196, v196, v197
	v_cndmask_b32_e64 v203, v194, -v196, s[76:77]
	v_mul_f32_e32 v190, v160, v178
	v_mul_f32_e32 v191, v161, v179
	v_mul_f32_e32 v192, v160, v179
	v_mul_f32_e32 v193, v161, v178
	v_sub_f32_e32 v190, v190, v191
	v_add_f32_e32 v192, v192, v193
	v_cndmask_b32_e64 v204, v190, -v192, s[76:77]
	v_mul_f32_e32 v194, v162, v180
	v_mul_f32_e32 v195, v163, v181
	v_mul_f32_e32 v196, v162, v181
	v_mul_f32_e32 v197, v163, v180
	v_sub_f32_e32 v194, v194, v195
	v_add_f32_e32 v196, v196, v197
	v_cndmask_b32_e64 v205, v194, -v196, s[76:77]
	v_mul_f32_e32 v190, v164, v182
	v_mul_f32_e32 v191, v165, v183
	v_mul_f32_e32 v192, v164, v183
	v_mul_f32_e32 v193, v165, v182
	v_sub_f32_e32 v190, v190, v191
	v_add_f32_e32 v192, v192, v193
	v_cndmask_b32_e64 v206, v190, -v192, s[76:77]
	v_mul_f32_e32 v194, v166, v184
	v_mul_f32_e32 v195, v167, v185
	v_mul_f32_e32 v196, v166, v185
	v_mul_f32_e32 v197, v167, v184
	v_sub_f32_e32 v194, v194, v195
	v_add_f32_e32 v196, v196, v197
	v_cndmask_b32_e64 v207, v194, -v196, s[76:77]
	v_cvt_pk_bf16_f32 v210, v200, v201
	v_cvt_pk_bf16_f32 v211, v202, v203
	v_cvt_pk_bf16_f32 v212, v204, v205
	v_cvt_pk_bf16_f32 v213, v206, v207
	global_store_dwordx4 v168, v[210:213], s[74:75]
	s_add_u32 s74, s74, 0x6000
	s_addc_u32 s75, s75, 0
	ds_read_b128 v[170:173], v151 offset:1024
	ds_read_b128 v[174:177], v151 offset:1040
	ds_read_b128 v[178:181], v151 offset:1056
	ds_read_b128 v[182:185], v151 offset:1072
	s_waitcnt lgkmcnt(0)
	v_mul_f32_e32 v190, v152, v170
	v_mul_f32_e32 v191, v153, v171
	v_mul_f32_e32 v192, v152, v171
	v_mul_f32_e32 v193, v153, v170
	v_sub_f32_e32 v190, v190, v191
	v_add_f32_e32 v192, v192, v193
	v_cndmask_b32_e64 v200, v190, -v192, s[76:77]
	v_mul_f32_e32 v194, v154, v172
	v_mul_f32_e32 v195, v155, v173
	v_mul_f32_e32 v196, v154, v173
	v_mul_f32_e32 v197, v155, v172
	v_sub_f32_e32 v194, v194, v195
	v_add_f32_e32 v196, v196, v197
	v_cndmask_b32_e64 v201, v194, -v196, s[76:77]
	v_mul_f32_e32 v190, v156, v174
	v_mul_f32_e32 v191, v157, v175
	v_mul_f32_e32 v192, v156, v175
	v_mul_f32_e32 v193, v157, v174
	v_sub_f32_e32 v190, v190, v191
	v_add_f32_e32 v192, v192, v193
	v_cndmask_b32_e64 v202, v190, -v192, s[76:77]
	v_mul_f32_e32 v194, v158, v176
	v_mul_f32_e32 v195, v159, v177
	v_mul_f32_e32 v196, v158, v177
	v_mul_f32_e32 v197, v159, v176
	v_sub_f32_e32 v194, v194, v195
	v_add_f32_e32 v196, v196, v197
	v_cndmask_b32_e64 v203, v194, -v196, s[76:77]
	v_mul_f32_e32 v190, v160, v178
	v_mul_f32_e32 v191, v161, v179
	v_mul_f32_e32 v192, v160, v179
	v_mul_f32_e32 v193, v161, v178
	v_sub_f32_e32 v190, v190, v191
	v_add_f32_e32 v192, v192, v193
	v_cndmask_b32_e64 v204, v190, -v192, s[76:77]
	v_mul_f32_e32 v194, v162, v180
	v_mul_f32_e32 v195, v163, v181
	v_mul_f32_e32 v196, v162, v181
	v_mul_f32_e32 v197, v163, v180
	v_sub_f32_e32 v194, v194, v195
	v_add_f32_e32 v196, v196, v197
	v_cndmask_b32_e64 v205, v194, -v196, s[76:77]
	v_mul_f32_e32 v190, v164, v182
	v_mul_f32_e32 v191, v165, v183
	v_mul_f32_e32 v192, v164, v183
	v_mul_f32_e32 v193, v165, v182
	v_sub_f32_e32 v190, v190, v191
	v_add_f32_e32 v192, v192, v193
	v_cndmask_b32_e64 v206, v190, -v192, s[76:77]
	v_mul_f32_e32 v194, v166, v184
	v_mul_f32_e32 v195, v167, v185
	v_mul_f32_e32 v196, v166, v185
	v_mul_f32_e32 v197, v167, v184
	v_sub_f32_e32 v194, v194, v195
	v_add_f32_e32 v196, v196, v197
	v_cndmask_b32_e64 v207, v194, -v196, s[76:77]
	v_cvt_pk_bf16_f32 v210, v200, v201
	v_cvt_pk_bf16_f32 v211, v202, v203
	v_cvt_pk_bf16_f32 v212, v204, v205
	v_cvt_pk_bf16_f32 v213, v206, v207
	global_store_dwordx4 v168, v[210:213], s[74:75]
	s_add_u32 s74, s74, 0x6000
	s_addc_u32 s75, s75, 0
	ds_read_b128 v[170:173], v151 offset:2048
	ds_read_b128 v[174:177], v151 offset:2064
	ds_read_b128 v[178:181], v151 offset:2080
	ds_read_b128 v[182:185], v151 offset:2096
	s_waitcnt lgkmcnt(0)
; __device__ __forceinline__ unsigned pk2(float lo, float hi) { return f2bf(lo) | (f2bf(hi) << 16); }
; __global__ void __launch_bounds__(NWAVES * 64, 2) fwd_kernel(Args args) {
;     ...
;                     else { const int n = (col - 256) & 63; const float cr = cc[(p * 64 + n) * 2], ci = cc[(p * 64 + n) * 2 + 1], ar = ap[((t + 1) * 64 + n) * 2], ai = ap[((t + 1) * 64 + n) * 2 + 1];
;                         v[e] = (col < 320) ? (cr * ar - ci * ai) : -(cr * ai + ci * ar); } }
;                 *(unsigned*)(W2 + (size_t)row * 384 + c0) = pk2(v[0], v[1]); }
	v_mul_f32_e32 v190, v152, v170
	v_mul_f32_e32 v191, v153, v171
	v_mul_f32_e32 v192, v152, v171
	v_mul_f32_e32 v193, v153, v170
	v_sub_f32_e32 v190, v190, v191
	v_add_f32_e32 v192, v192, v193
	v_cndmask_b32_e64 v200, v190, -v192, s[76:77]
	v_mul_f32_e32 v194, v154, v172
	v_mul_f32_e32 v195, v155, v173
	v_mul_f32_e32 v196, v154, v173
	v_mul_f32_e32 v197, v155, v172
	v_sub_f32_e32 v194, v194, v195
	v_add_f32_e32 v196, v196, v197
	v_cndmask_b32_e64 v201, v194, -v196, s[76:77]
	v_mul_f32_e32 v190, v156, v174
	v_mul_f32_e32 v191, v157, v175
	v_mul_f32_e32 v192, v156, v175
	v_mul_f32_e32 v193, v157, v174
	v_sub_f32_e32 v190, v190, v191
	v_add_f32_e32 v192, v192, v193
	v_cndmask_b32_e64 v202, v190, -v192, s[76:77]
	v_mul_f32_e32 v194, v158, v176
	v_mul_f32_e32 v195, v159, v177
	v_mul_f32_e32 v196, v158, v177
	v_mul_f32_e32 v197, v159, v176
	v_sub_f32_e32 v194, v194, v195
	v_add_f32_e32 v196, v196, v197
	v_cndmask_b32_e64 v203, v194, -v196, s[76:77]
	v_mul_f32_e32 v190, v160, v178
	v_mul_f32_e32 v191, v161, v179
	v_mul_f32_e32 v192, v160, v179
	v_mul_f32_e32 v193, v161, v178
	v_sub_f32_e32 v190, v190, v191
	v_add_f32_e32 v192, v192, v193
	v_cndmask_b32_e64 v204, v190, -v192, s[76:77]
	v_mul_f32_e32 v194, v162, v180
	v_mul_f32_e32 v195, v163, v181
	v_mul_f32_e32 v196, v162, v181
	v_mul_f32_e32 v197, v163, v180
	v_sub_f32_e32 v194, v194, v195
	v_add_f32_e32 v196, v196, v197
	v_cndmask_b32_e64 v205, v194, -v196, s[76:77]
	v_mul_f32_e32 v190, v164, v182
	v_mul_f32_e32 v191, v165, v183
	v_mul_f32_e32 v192, v164, v183
	v_mul_f32_e32 v193, v165, v182
	v_sub_f32_e32 v190, v190, v191
	v_add_f32_e32 v192, v192, v193
	v_cndmask_b32_e64 v206, v190, -v192, s[76:77]
	v_mul_f32_e32 v194, v166, v184
	v_mul_f32_e32 v195, v167, v185
	v_mul_f32_e32 v196, v166, v185
	v_mul_f32_e32 v197, v167, v184
	v_sub_f32_e32 v194, v194, v195
	v_add_f32_e32 v196, v196, v197
	v_cndmask_b32_e64 v207, v194, -v196, s[76:77]
	v_cvt_pk_bf16_f32 v210, v200, v201
	v_cvt_pk_bf16_f32 v211, v202, v203
	v_cvt_pk_bf16_f32 v212, v204, v205
	v_cvt_pk_bf16_f32 v213, v206, v207
	global_store_dwordx4 v168, v[210:213], s[74:75]
	s_add_u32 s74, s74, 0x6000
	s_addc_u32 s75, s75, 0
	ds_read_b128 v[170:173], v151 offset:3072
	ds_read_b128 v[174:177], v151 offset:3088
	ds_read_b128 v[178:181], v151 offset:3104
	ds_read_b128 v[182:185], v151 offset:3120
	s_waitcnt lgkmcnt(0)
	v_mul_f32_e32 v190, v152, v170
	v_mul_f32_e32 v191, v153, v171
	v_mul_f32_e32 v192, v152, v171
	v_mul_f32_e32 v193, v153, v170
	v_sub_f32_e32 v190, v190, v191
	v_add_f32_e32 v192, v192, v193
	v_cndmask_b32_e64 v200, v190, -v192, s[76:77]
	v_mul_f32_e32 v194, v154, v172
	v_mul_f32_e32 v195, v155, v173
	v_mul_f32_e32 v196, v154, v173
	v_mul_f32_e32 v197, v155, v172
	v_sub_f32_e32 v194, v194, v195
	v_add_f32_e32 v196, v196, v197
	v_cndmask_b32_e64 v201, v194, -v196, s[76:77]
	v_mul_f32_e32 v190, v156, v174
	v_mul_f32_e32 v191, v157, v175
	v_mul_f32_e32 v192, v156, v175
	v_mul_f32_e32 v193, v157, v174
	v_sub_f32_e32 v190, v190, v191
	v_add_f32_e32 v192, v192, v193
	v_cndmask_b32_e64 v202, v190, -v192, s[76:77]
	v_mul_f32_e32 v194, v158, v176
	v_mul_f32_e32 v195, v159, v177
	v_mul_f32_e32 v196, v158, v177
	v_mul_f32_e32 v197, v159, v176
	v_sub_f32_e32 v194, v194, v195
	v_add_f32_e32 v196, v196, v197
	v_cndmask_b32_e64 v203, v194, -v196, s[76:77]
	v_mul_f32_e32 v190, v160, v178
	v_mul_f32_e32 v191, v161, v179
	v_mul_f32_e32 v192, v160, v179
	v_mul_f32_e32 v193, v161, v178
	v_sub_f32_e32 v190, v190, v191
	v_add_f32_e32 v192, v192, v193
	v_cndmask_b32_e64 v204, v190, -v192, s[76:77]
	v_mul_f32_e32 v194, v162, v180
	v_mul_f32_e32 v195, v163, v181
	v_mul_f32_e32 v196, v162, v181
	v_mul_f32_e32 v197, v163, v180
	v_sub_f32_e32 v194, v194, v195
	v_add_f32_e32 v196, v196, v197
	v_cndmask_b32_e64 v205, v194, -v196, s[76:77]
	v_mul_f32_e32 v190, v164, v182
	v_mul_f32_e32 v191, v165, v183
	v_mul_f32_e32 v192, v164, v183
	v_mul_f32_e32 v193, v165, v182
	v_sub_f32_e32 v190, v190, v191
	v_add_f32_e32 v192, v192, v193
	v_cndmask_b32_e64 v206, v190, -v192, s[76:77]
	v_mul_f32_e32 v194, v166, v184
	v_mul_f32_e32 v195, v167, v185
	v_mul_f32_e32 v196, v166, v185
	v_mul_f32_e32 v197, v167, v184
	v_sub_f32_e32 v194, v194, v195
	v_add_f32_e32 v196, v196, v197
	v_cndmask_b32_e64 v207, v194, -v196, s[76:77]
	v_cvt_pk_bf16_f32 v210, v200, v201
	v_cvt_pk_bf16_f32 v211, v202, v203
	v_cvt_pk_bf16_f32 v212, v204, v205
	v_cvt_pk_bf16_f32 v213, v206, v207
	global_store_dwordx4 v168, v[210:213], s[74:75]
	s_add_u32 s74, s74, 0x6000
	s_addc_u32 s75, s75, 0
	ds_read_b128 v[170:173], v151 offset:4096
	ds_read_b128 v[174:177], v151 offset:4112
	ds_read_b128 v[178:181], v151 offset:4128
	ds_read_b128 v[182:185], v151 offset:4144
	s_waitcnt lgkmcnt(0)
; __device__ __forceinline__ unsigned pk2(float lo, float hi) { return f2bf(lo) | (f2bf(hi) << 16); }
; __global__ void __launch_bounds__(NWAVES * 64, 2) fwd_kernel(Args args) {
;     ...
;                     else { const int n = (col - 256) & 63; const float cr = cc[(p * 64 + n) * 2], ci = cc[(p * 64 + n) * 2 + 1], ar = ap[((t + 1) * 64 + n) * 2], ai = ap[((t + 1) * 64 + n) * 2 + 1];
;                         v[e] = (col < 320) ? (cr * ar - ci * ai) : -(cr * ai + ci * ar); } }
;                 *(unsigned*)(W2 + (size_t)row * 384 + c0) = pk2(v[0], v[1]); }
	v_mul_f32_e32 v190, v152, v170
	v_mul_f32_e32 v191, v153, v171
	v_mul_f32_e32 v192, v152, v171
	v_mul_f32_e32 v193, v153, v170
	v_sub_f32_e32 v190, v190, v191
	v_add_f32_e32 v192, v192, v193
	v_cndmask_b32_e64 v200, v190, -v192, s[76:77]
	v_mul_f32_e32 v194, v154, v172
	v_mul_f32_e32 v195, v155, v173
	v_mul_f32_e32 v196, v154, v173
	v_mul_f32_e32 v197, v155, v172
	v_sub_f32_e32 v194, v194, v195
	v_add_f32_e32 v196, v196, v197
	v_cndmask_b32_e64 v201, v194, -v196, s[76:77]
	v_mul_f32_e32 v190, v156, v174
	v_mul_f32_e32 v191, v157, v175
	v_mul_f32_e32 v192, v156, v175
	v_mul_f32_e32 v193, v157, v174
	v_sub_f32_e32 v190, v190, v191
	v_add_f32_e32 v192, v192, v193
	v_cndmask_b32_e64 v202, v190, -v192, s[76:77]
	v_mul_f32_e32 v194, v158, v176
	v_mul_f32_e32 v195, v159, v177
	v_mul_f32_e32 v196, v158, v177
	v_mul_f32_e32 v197, v159, v176
	v_sub_f32_e32 v194, v194, v195
	v_add_f32_e32 v196, v196, v197
	v_cndmask_b32_e64 v203, v194, -v196, s[76:77]
	v_mul_f32_e32 v190, v160, v178
	v_mul_f32_e32 v191, v161, v179
	v_mul_f32_e32 v192, v160, v179
	v_mul_f32_e32 v193, v161, v178
	v_sub_f32_e32 v190, v190, v191
	v_add_f32_e32 v192, v192, v193
	v_cndmask_b32_e64 v204, v190, -v192, s[76:77]
	v_mul_f32_e32 v194, v162, v180
	v_mul_f32_e32 v195, v163, v181
	v_mul_f32_e32 v196, v162, v181
	v_mul_f32_e32 v197, v163, v180
	v_sub_f32_e32 v194, v194, v195
	v_add_f32_e32 v196, v196, v197
	v_cndmask_b32_e64 v205, v194, -v196, s[76:77]
	v_mul_f32_e32 v190, v164, v182
	v_mul_f32_e32 v191, v165, v183
	v_mul_f32_e32 v192, v164, v183
	v_mul_f32_e32 v193, v165, v182
	v_sub_f32_e32 v190, v190, v191
	v_add_f32_e32 v192, v192, v193
	v_cndmask_b32_e64 v206, v190, -v192, s[76:77]
	v_mul_f32_e32 v194, v166, v184
	v_mul_f32_e32 v195, v167, v185
	v_mul_f32_e32 v196, v166, v185
	v_mul_f32_e32 v197, v167, v184
	v_sub_f32_e32 v194, v194, v195
	v_add_f32_e32 v196, v196, v197
	v_cndmask_b32_e64 v207, v194, -v196, s[76:77]
	v_cvt_pk_bf16_f32 v210, v200, v201
	v_cvt_pk_bf16_f32 v211, v202, v203
	v_cvt_pk_bf16_f32 v212, v204, v205
	v_cvt_pk_bf16_f32 v213, v206, v207
	global_store_dwordx4 v168, v[210:213], s[74:75]
	s_add_u32 s74, s74, 0x6000
	s_addc_u32 s75, s75, 0
	ds_read_b128 v[170:173], v151 offset:5120
	ds_read_b128 v[174:177], v151 offset:5136
	ds_read_b128 v[178:181], v151 offset:5152
	ds_read_b128 v[182:185], v151 offset:5168
	s_waitcnt lgkmcnt(0)
	v_mul_f32_e32 v190, v152, v170
	v_mul_f32_e32 v191, v153, v171
	v_mul_f32_e32 v192, v152, v171
	v_mul_f32_e32 v193, v153, v170
	v_sub_f32_e32 v190, v190, v191
	v_add_f32_e32 v192, v192, v193
	v_cndmask_b32_e64 v200, v190, -v192, s[76:77]
	v_mul_f32_e32 v194, v154, v172
	v_mul_f32_e32 v195, v155, v173
	v_mul_f32_e32 v196, v154, v173
	v_mul_f32_e32 v197, v155, v172
	v_sub_f32_e32 v194, v194, v195
	v_add_f32_e32 v196, v196, v197
	v_cndmask_b32_e64 v201, v194, -v196, s[76:77]
	v_mul_f32_e32 v190, v156, v174
	v_mul_f32_e32 v191, v157, v175
	v_mul_f32_e32 v192, v156, v175
	v_mul_f32_e32 v193, v157, v174
	v_sub_f32_e32 v190, v190, v191
	v_add_f32_e32 v192, v192, v193
	v_cndmask_b32_e64 v202, v190, -v192, s[76:77]
	v_mul_f32_e32 v194, v158, v176
	v_mul_f32_e32 v195, v159, v177
	v_mul_f32_e32 v196, v158, v177
	v_mul_f32_e32 v197, v159, v176
	v_sub_f32_e32 v194, v194, v195
	v_add_f32_e32 v196, v196, v197
	v_cndmask_b32_e64 v203, v194, -v196, s[76:77]
	v_mul_f32_e32 v190, v160, v178
	v_mul_f32_e32 v191, v161, v179
	v_mul_f32_e32 v192, v160, v179
	v_mul_f32_e32 v193, v161, v178
	v_sub_f32_e32 v190, v190, v191
	v_add_f32_e32 v192, v192, v193
	v_cndmask_b32_e64 v204, v190, -v192, s[76:77]
	v_mul_f32_e32 v194, v162, v180
	v_mul_f32_e32 v195, v163, v181
	v_mul_f32_e32 v196, v162, v181
	v_mul_f32_e32 v197, v163, v180
	v_sub_f32_e32 v194, v194, v195
	v_add_f32_e32 v196, v196, v197
	v_cndmask_b32_e64 v205, v194, -v196, s[76:77]
	v_mul_f32_e32 v190, v164, v182
	v_mul_f32_e32 v191, v165, v183
	v_mul_f32_e32 v192, v164, v183
	v_mul_f32_e32 v193, v165, v182
	v_sub_f32_e32 v190, v190, v191
	v_add_f32_e32 v192, v192, v193
	v_cndmask_b32_e64 v206, v190, -v192, s[76:77]
	v_mul_f32_e32 v194, v166, v184
	v_mul_f32_e32 v195, v167, v185
	v_mul_f32_e32 v196, v166, v185
	v_mul_f32_e32 v197, v167, v184
	v_sub_f32_e32 v194, v194, v195
	v_add_f32_e32 v196, v196, v197
	v_cndmask_b32_e64 v207, v194, -v196, s[76:77]
	v_cvt_pk_bf16_f32 v210, v200, v201
	v_cvt_pk_bf16_f32 v211, v202, v203
	v_cvt_pk_bf16_f32 v212, v204, v205
	v_cvt_pk_bf16_f32 v213, v206, v207
	global_store_dwordx4 v168, v[210:213], s[74:75]
	s_add_u32 s74, s74, 0x6000
	s_addc_u32 s75, s75, 0
	ds_read_b128 v[170:173], v151 offset:6144
	ds_read_b128 v[174:177], v151 offset:6160
	ds_read_b128 v[178:181], v151 offset:6176
	ds_read_b128 v[182:185], v151 offset:6192
	s_waitcnt lgkmcnt(0)
; __device__ __forceinline__ unsigned pk2(float lo, float hi) { return f2bf(lo) | (f2bf(hi) << 16); }
; __global__ void __launch_bounds__(NWAVES * 64, 2) fwd_kernel(Args args) {
;     ...
;                     else { const int n = (col - 256) & 63; const float cr = cc[(p * 64 + n) * 2], ci = cc[(p * 64 + n) * 2 + 1], ar = ap[((t + 1) * 64 + n) * 2], ai = ap[((t + 1) * 64 + n) * 2 + 1];
;                         v[e] = (col < 320) ? (cr * ar - ci * ai) : -(cr * ai + ci * ar); } }
;                 *(unsigned*)(W2 + (size_t)row * 384 + c0) = pk2(v[0], v[1]); }
	v_mul_f32_e32 v190, v152, v170
	v_mul_f32_e32 v191, v153, v171
	v_mul_f32_e32 v192, v152, v171
	v_mul_f32_e32 v193, v153, v170
	v_sub_f32_e32 v190, v190, v191
	v_add_f32_e32 v192, v192, v193
	v_cndmask_b32_e64 v200, v190, -v192, s[76:77]
	v_mul_f32_e32 v194, v154, v172
	v_mul_f32_e32 v195, v155, v173
	v_mul_f32_e32 v196, v154, v173
	v_mul_f32_e32 v197, v155, v172
	v_sub_f32_e32 v194, v194, v195
	v_add_f32_e32 v196, v196, v197
	v_cndmask_b32_e64 v201, v194, -v196, s[76:77]
	v_mul_f32_e32 v190, v156, v174
	v_mul_f32_e32 v191, v157, v175
	v_mul_f32_e32 v192, v156, v175
	v_mul_f32_e32 v193, v157, v174
	v_sub_f32_e32 v190, v190, v191
	v_add_f32_e32 v192, v192, v193
	v_cndmask_b32_e64 v202, v190, -v192, s[76:77]
	v_mul_f32_e32 v194, v158, v176
	v_mul_f32_e32 v195, v159, v177
	v_mul_f32_e32 v196, v158, v177
	v_mul_f32_e32 v197, v159, v176
	v_sub_f32_e32 v194, v194, v195
	v_add_f32_e32 v196, v196, v197
	v_cndmask_b32_e64 v203, v194, -v196, s[76:77]
	v_mul_f32_e32 v190, v160, v178
	v_mul_f32_e32 v191, v161, v179
	v_mul_f32_e32 v192, v160, v179
	v_mul_f32_e32 v193, v161, v178
	v_sub_f32_e32 v190, v190, v191
	v_add_f32_e32 v192, v192, v193
	v_cndmask_b32_e64 v204, v190, -v192, s[76:77]
	v_mul_f32_e32 v194, v162, v180
	v_mul_f32_e32 v195, v163, v181
	v_mul_f32_e32 v196, v162, v181
	v_mul_f32_e32 v197, v163, v180
	v_sub_f32_e32 v194, v194, v195
	v_add_f32_e32 v196, v196, v197
	v_cndmask_b32_e64 v205, v194, -v196, s[76:77]
	v_mul_f32_e32 v190, v164, v182
	v_mul_f32_e32 v191, v165, v183
	v_mul_f32_e32 v192, v164, v183
	v_mul_f32_e32 v193, v165, v182
	v_sub_f32_e32 v190, v190, v191
	v_add_f32_e32 v192, v192, v193
	v_cndmask_b32_e64 v206, v190, -v192, s[76:77]
	v_mul_f32_e32 v194, v166, v184
	v_mul_f32_e32 v195, v167, v185
	v_mul_f32_e32 v196, v166, v185
	v_mul_f32_e32 v197, v167, v184
	v_sub_f32_e32 v194, v194, v195
	v_add_f32_e32 v196, v196, v197
	v_cndmask_b32_e64 v207, v194, -v196, s[76:77]
	v_cvt_pk_bf16_f32 v210, v200, v201
	v_cvt_pk_bf16_f32 v211, v202, v203
	v_cvt_pk_bf16_f32 v212, v204, v205
	v_cvt_pk_bf16_f32 v213, v206, v207
	global_store_dwordx4 v168, v[210:213], s[74:75]
	s_add_u32 s74, s74, 0x6000
	s_addc_u32 s75, s75, 0
	ds_read_b128 v[170:173], v151 offset:7168
	ds_read_b128 v[174:177], v151 offset:7184
	ds_read_b128 v[178:181], v151 offset:7200
	ds_read_b128 v[182:185], v151 offset:7216
	s_waitcnt lgkmcnt(0)
	v_mul_f32_e32 v190, v152, v170
	v_mul_f32_e32 v191, v153, v171
	v_mul_f32_e32 v192, v152, v171
	v_mul_f32_e32 v193, v153, v170
	v_sub_f32_e32 v190, v190, v191
	v_add_f32_e32 v192, v192, v193
	v_cndmask_b32_e64 v200, v190, -v192, s[76:77]
	v_mul_f32_e32 v194, v154, v172
	v_mul_f32_e32 v195, v155, v173
	v_mul_f32_e32 v196, v154, v173
	v_mul_f32_e32 v197, v155, v172
	v_sub_f32_e32 v194, v194, v195
	v_add_f32_e32 v196, v196, v197
	v_cndmask_b32_e64 v201, v194, -v196, s[76:77]
	v_mul_f32_e32 v190, v156, v174
	v_mul_f32_e32 v191, v157, v175
	v_mul_f32_e32 v192, v156, v175
	v_mul_f32_e32 v193, v157, v174
	v_sub_f32_e32 v190, v190, v191
	v_add_f32_e32 v192, v192, v193
	v_cndmask_b32_e64 v202, v190, -v192, s[76:77]
	v_mul_f32_e32 v194, v158, v176
	v_mul_f32_e32 v195, v159, v177
	v_mul_f32_e32 v196, v158, v177
	v_mul_f32_e32 v197, v159, v176
	v_sub_f32_e32 v194, v194, v195
	v_add_f32_e32 v196, v196, v197
	v_cndmask_b32_e64 v203, v194, -v196, s[76:77]
	v_mul_f32_e32 v190, v160, v178
	v_mul_f32_e32 v191, v161, v179
	v_mul_f32_e32 v192, v160, v179
	v_mul_f32_e32 v193, v161, v178
	v_sub_f32_e32 v190, v190, v191
	v_add_f32_e32 v192, v192, v193
	v_cndmask_b32_e64 v204, v190, -v192, s[76:77]
	v_mul_f32_e32 v194, v162, v180
	v_mul_f32_e32 v195, v163, v181
	v_mul_f32_e32 v196, v162, v181
	v_mul_f32_e32 v197, v163, v180
	v_sub_f32_e32 v194, v194, v195
	v_add_f32_e32 v196, v196, v197
	v_cndmask_b32_e64 v205, v194, -v196, s[76:77]
	v_mul_f32_e32 v190, v164, v182
	v_mul_f32_e32 v191, v165, v183
	v_mul_f32_e32 v192, v164, v183
	v_mul_f32_e32 v193, v165, v182
	v_sub_f32_e32 v190, v190, v191
	v_add_f32_e32 v192, v192, v193
	v_cndmask_b32_e64 v206, v190, -v192, s[76:77]
	v_mul_f32_e32 v194, v166, v184
	v_mul_f32_e32 v195, v167, v185
	v_mul_f32_e32 v196, v166, v185
	v_mul_f32_e32 v197, v167, v184
	v_sub_f32_e32 v194, v194, v195
	v_add_f32_e32 v196, v196, v197
	v_cndmask_b32_e64 v207, v194, -v196, s[76:77]
	v_cvt_pk_bf16_f32 v210, v200, v201
	v_cvt_pk_bf16_f32 v211, v202, v203
	v_cvt_pk_bf16_f32 v212, v204, v205
	v_cvt_pk_bf16_f32 v213, v206, v207
	global_store_dwordx4 v168, v[210:213], s[74:75]
	s_add_u32 s74, s74, 0x6000
	s_addc_u32 s75, s75, 0
